# replace cg grid.sync after P0 with single-counter barrier (on top of v22)
# baseline (speedup 1.0000x reference)
; __global__ void __launch_bounds__(512, 2) hybrid_fwd(Params p) {
;     ...
;     grid.sync();
.LBB0_190:
	s_or_b64 exec, exec, s[4:5]
	v_lshrrev_b32_e32 v1, 20, v0
	v_lshrrev_b32_e32 v0, 10, v0
	v_or_b32_e32 v0, v0, v1
	s_movk_i32 s0, 0x3ff
	v_and_or_b32 v0, v0, s0, v254
	v_cmp_eq_u32_e32 vcc, 0, v0
	s_barrier
	s_and_saveexec_b64 s[4:5], vcc
	s_cbranch_execz .LBB0_200
	buffer_wbl2 sc1
	s_waitcnt vmcnt(0)
	v_mov_b32_e32 v2, 0x36b0
	v_mov_b32_e32 v1, 1
	global_atomic_add v2, v1, s[78:79]
.Lgs_spin:
	s_sleep 2
	global_load_dword v3, v2, s[78:79] sc1
	s_waitcnt vmcnt(0)
	v_readfirstlane_b32 s6, v3
	s_nop 1
	s_cmp_lt_u32 s6, s3
	s_cbranch_scc1 .Lgs_spin
